# v92 plus even spread of the PV filler VALU over the MFMA gaps in the diff attention loop only
# speedup vs baseline: 1.0038x; 1.0038x over previous
.Latt_diff_norescale:
	v_exp_f32_e32 v64, v64
	v_exp_f32_e32 v65, v65
	v_exp_f32_e32 v66, v66
	v_exp_f32_e32 v67, v67
	v_exp_f32_e32 v68, v68
	v_exp_f32_e32 v69, v69
	v_exp_f32_e32 v70, v70
	v_exp_f32_e32 v71, v71
	v_cvt_pk_bf16_f32 v218, v64, v65
	v_cvt_pk_bf16_f32 v219, v66, v67
	v_cvt_pk_bf16_f32 v220, v68, v69
	v_cvt_pk_bf16_f32 v221, v70, v71
	s_waitcnt lgkmcnt(2)
	s_nop 0
	v_mfma_f32_32x32x16_bf16 v[0:15], v[112:115], v[218:221], v[0:15]
	ds_read_b128 v[112:115], v243 offset:27680
	v_exp_f32_e32 v72, v72
	v_exp_f32_e32 v73, v73
	v_add_f32_e32 v226, v64, v68
	v_mfma_f32_32x32x16_bf16 v[48:63], v[116:119], v[218:221], v[48:63]
	ds_read_b128 v[116:119], v243 offset:32288
	v_exp_f32_e32 v74, v74
	v_exp_f32_e32 v75, v75
	v_cvt_pk_bf16_f32 v222, v72, v73
	v_add_f32_e32 v227, v65, v69
	s_waitcnt lgkmcnt(2)
	v_mfma_f32_32x32x16_bf16 v[32:47], v[120:123], v[218:221], v[32:47]
	ds_read_b128 v[120:123], v243 offset:36896
	v_exp_f32_e32 v76, v76
	v_exp_f32_e32 v77, v77
	v_cvt_pk_bf16_f32 v223, v74, v75
	v_add_f32_e32 v228, v66, v70
	v_mfma_f32_32x32x16_bf16 v[16:31], v[124:127], v[218:221], v[16:31]
	ds_read_b128 v[124:127], v243 offset:41504
	v_exp_f32_e32 v78, v78
	v_exp_f32_e32 v79, v79
	v_cvt_pk_bf16_f32 v224, v76, v77
	v_cvt_pk_bf16_f32 v225, v78, v79
	v_add_f32_e32 v229, v67, v71
	s_waitcnt lgkmcnt(2)
	v_mfma_f32_32x32x16_bf16 v[0:15], v[112:115], v[222:225], v[0:15]
	ds_read_b128 v[112:115], v243 offset:27712
	v_exp_f32_e32 v80, v80
	v_exp_f32_e32 v81, v81
	v_add_f32_e32 v226, v226, v72
	v_add_f32_e32 v227, v227, v73
	v_add_f32_e32 v228, v228, v74
	v_mfma_f32_32x32x16_bf16 v[48:63], v[116:119], v[222:225], v[48:63]
	ds_read_b128 v[116:119], v243 offset:32320
	v_exp_f32_e32 v82, v82
	v_exp_f32_e32 v83, v83
	v_cvt_pk_bf16_f32 v218, v80, v81
	v_add_f32_e32 v229, v229, v75
	v_add_f32_e32 v226, v226, v76
	s_waitcnt lgkmcnt(2)
	v_mfma_f32_32x32x16_bf16 v[32:47], v[120:123], v[222:225], v[32:47]
	ds_read_b128 v[120:123], v243 offset:36928
	v_exp_f32_e32 v84, v84
	v_exp_f32_e32 v85, v85
	v_cvt_pk_bf16_f32 v219, v82, v83
	v_add_f32_e32 v227, v227, v77
	v_add_f32_e32 v228, v228, v78
	v_mfma_f32_32x32x16_bf16 v[16:31], v[124:127], v[222:225], v[16:31]
	ds_read_b128 v[124:127], v243 offset:41536
	v_exp_f32_e32 v86, v86
	v_exp_f32_e32 v87, v87
	v_cvt_pk_bf16_f32 v220, v84, v85
	v_cvt_pk_bf16_f32 v221, v86, v87
	v_add_f32_e32 v229, v229, v79
	s_waitcnt lgkmcnt(2)
	v_mfma_f32_32x32x16_bf16 v[0:15], v[112:115], v[218:221], v[0:15]
	ds_read_b128 v[112:115], v243 offset:27744
	v_exp_f32_e32 v88, v88
	v_exp_f32_e32 v89, v89
	v_add_f32_e32 v226, v226, v80
	v_add_f32_e32 v227, v227, v81
	v_add_f32_e32 v228, v228, v82
	v_mfma_f32_32x32x16_bf16 v[48:63], v[116:119], v[218:221], v[48:63]
	ds_read_b128 v[116:119], v243 offset:32352
	v_exp_f32_e32 v90, v90
	v_exp_f32_e32 v91, v91
	v_cvt_pk_bf16_f32 v222, v88, v89
	v_add_f32_e32 v229, v229, v83
	v_add_f32_e32 v226, v226, v84
	s_waitcnt lgkmcnt(2)
	v_mfma_f32_32x32x16_bf16 v[32:47], v[120:123], v[218:221], v[32:47]
	ds_read_b128 v[120:123], v243 offset:36960
	v_exp_f32_e32 v92, v92
	v_exp_f32_e32 v93, v93
	v_cvt_pk_bf16_f32 v223, v90, v91
	v_add_f32_e32 v227, v227, v85
	v_add_f32_e32 v228, v228, v86
	v_mfma_f32_32x32x16_bf16 v[16:31], v[124:127], v[218:221], v[16:31]
	ds_read_b128 v[124:127], v243 offset:41568
	v_exp_f32_e32 v94, v94
	v_exp_f32_e32 v95, v95
	v_cvt_pk_bf16_f32 v224, v92, v93
	v_cvt_pk_bf16_f32 v225, v94, v95
	v_add_f32_e32 v229, v229, v87
	s_waitcnt lgkmcnt(2)
	v_mfma_f32_32x32x16_bf16 v[0:15], v[112:115], v[222:225], v[0:15]
	v_add_f32_e32 v226, v226, v88
	v_add_f32_e32 v227, v227, v89
	v_mfma_f32_32x32x16_bf16 v[48:63], v[116:119], v[222:225], v[48:63]
	v_add_f32_e32 v228, v228, v90
	v_add_f32_e32 v229, v229, v91
	s_waitcnt lgkmcnt(0)
	v_mfma_f32_32x32x16_bf16 v[32:47], v[120:123], v[222:225], v[32:47]
	v_add_f32_e32 v226, v226, v92
	v_add_f32_e32 v227, v227, v93
	v_mfma_f32_32x32x16_bf16 v[16:31], v[124:127], v[222:225], v[16:31]
	v_add_f32_e32 v228, v228, v94
	v_add_f32_e32 v229, v229, v95
	v_add_f32_e32 v226, v226, v227
	v_add_f32_e32 v228, v228, v229
	v_add_f32_e32 v226, v226, v228
	v_add_f32_e32 v157, v157, v226
